# v23 + branch-B K tile LDS image: 16-row XOR swizzle (row&15) instead of (row&7) removes the 2-way ds_read_b128 bank conflict of the K fragment reads
# speedup vs baseline: 1.0052x; 1.0028x over previous
; __device__ __forceinline__ int v_rd_base(int lane) { return ((lane & 3) << 3) | (((lane >> 2) & 3) << 6) | (((lane >> 4) & 1) << 5) | (((lane >> 5) & 1) << 8); }
; template <int DK>
; __device__ __forceinline__ void qkt(f32x16& p0, f32x16& p1, const char* Ks, const bf16x8* qr, int r32, int hi) {
;   p0 = f32x16{}; p1 = f32x16{};
; #pragma unroll
;   for (int d0 = 0; d0 < DK / 16; ++d0) { const int cb = (d0 * 16 + hi * 8) * 2;
;     bf16x8 b0, b1;
;     if constexpr (DK == 128) { b0 = *reinterpret_cast<const bf16x8*>(Ks + KSWZ128(r32, cb)); b1 = *reinterpret_cast<const bf16x8*>(Ks + KSWZ128(32 + r32, cb)); }
;     else { b0 = *reinterpret_cast<const bf16x8*>(Ks + KSWZ64(r32, cb)); b1 = *reinterpret_cast<const bf16x8*>(Ks + KSWZ64(32 + r32, cb)); }
;     p0 = __builtin_amdgcn_mfma_f32_32x32x16_bf16(b0, qr[d0], p0, 0, 0, 0);
;     p1 = __builtin_amdgcn_mfma_f32_32x32x16_bf16(b1, qr[d0], p1, 0, 0, 0); }
; template <int DK, int LDK, bool BIAS, bool NOMAX> ...
;     ...
;   if constexpr (DK == 128) { { const int r = 4 * wid + (lane >> 4), c = (lane & 15) ^ (r & 7); koff0 = r * LDK + c * 8; }
;                              { const int r = 4 * (wid + 8) + (lane >> 4), c = (lane & 15) ^ (r & 7); koff1 = r * LDK + c * 8; } }
;   else { const int r = 8 * wid + (lane >> 3), c = (lane & 7) ^ ((r >> 1) & 7); koff0 = r * LDK + c * 8; }
;   { const int st = 2 * wid + (lane >> 5), kk = (st >> 2) * 8 + ((lane & 31) >> 2), k = (kk & ~0xC) | ((kk & 4) << 1) | ((kk & 8) >> 1); voff0 = k * LDK + (st & 3) * 32 + (lane & 3) * 8; }
;   { const int st = 2 * (wid + 8) + (lane >> 5), kk = (st >> 2) * 8 + ((lane & 31) >> 2), k = (kk & ~0xC) | ((kk & 4) << 1) | ((kk & 8) >> 1); voff1 = k * LDK + (st & 3) * 32 + (lane & 3) * 8; }
;   const bf16_t* ks0 = Kh + koff0; const bf16_t* ks1 = Kh + koff1; const bf16_t* vs0 = Vh + voff0; const bf16_t* vs1 = Vh + voff1;
;   const lds_uptr kdst = (lds_uptr)(K_lds + wid * 1024), vdst = (lds_uptr)(V_lds + wid * 1024);
;     ...
;   float curb = 0.f;
;   f32x16 pA0, pA1, pB0, pB1; float mnA, alA, alB; bf16x8 pa[4]; const int NT = seq / KVBLK;
;   const lds_cptr vp0 = (lds_cptr)V_lds + v_rd_base(lane);
;   const int vb0 = (int)(uintptr_t)V_lds + v_rd_base(lane);
;   WBAR(0);
;   DMA_K(0, 0); DMA_V(0, 0); DMA_K(1, SHM_K); DMA_K(2, 2 * SHM_K);
;   if constexpr (DK == 128) WBAR(6); else WBAR(4);
.LBB0_401:
	s_or_b64 exec, exec, s[0:1]
	s_and_b32 s0, s20, 0xffffe000
	s_lshr_b32 s3, s21, 5
	s_addk_i32 s0, 0x4000
	s_ashr_i32 s1, s0, 31
	s_and_b32 s3, s3, 4
	s_lshl_b64 s[0:1], s[0:1], 9
	s_lshl_b32 s3, s3, 6
	s_or_b32 s0, s0, s3
	s_add_u32 s42, s86, s0
	s_addc_u32 s43, s87, s1
	s_ashr_i32 s41, s40, 31
	s_lshl_b64 s[0:1], s[40:41], 9
	v_readlane_b32 s4, v249, 44
	v_readlane_b32 s5, v249, 45
	s_add_u32 s3, s4, s0
	s_addc_u32 s7, s5, s1
	v_readlane_b32 s4, v249, 42
	v_readlane_b32 s5, v249, 43
	s_add_u32 s0, s4, s0
	s_addc_u32 s1, s5, s1
	s_lshl_b32 s2, s2, 6
	s_and_b32 s2, s2, 0x100
	s_add_u32 s4, s0, s2
	s_addc_u32 s5, s1, 0
	v_mov_b32_e32 v50, v176
	s_add_u32 s6, s3, s2
	s_addc_u32 s7, s7, 0
	v_readfirstlane_b32 s0, v50
	s_ashr_i32 s2, s0, 6
	v_bfe_u32 v51, v50, 4, 2
	v_lshl_or_b32 v2, s2, 2, v51
	v_and_b32_e32 v3, 15, v50
	s_add_i32 s1, s2, 8
	v_and_b32_e32 v0, 31, v50
	v_bitop3_b32 v4, v2, v3, 15 bitop3:0x6c
	s_lshl_b32 s3, s1, 2
	s_ashr_i32 s10, s0, 4
	v_lshlrev_b32_e32 v52, 3, v4
	v_or_b32_e32 v4, s3, v51
	s_and_b32 s9, s10, -16
	v_bfe_u32 v54, v0, 2, 2
	v_lshrrev_b32_e32 v6, 1, v50
	s_lshr_b32 s10, s10, 1
	v_bfe_u32 v10, v50, 5, 1
	v_bitop3_b32 v3, v4, v3, 15 bitop3:0x6c
	s_lshl_b32 s8, s2, 1
	v_or_b32_e32 v5, s9, v54
	v_and_b32_e32 v55, 8, v6
	s_and_b32 s10, s10, 4
	v_lshlrev_b32_e32 v53, 3, v3
	v_bfe_u32 v3, v50, 2, 3
	v_or3_b32 v5, v5, s10, v55
	v_and_or_b32 v6, s8, 2, v10
	v_lshlrev_b32_e32 v7, 3, v50
	s_lshl_b32 s8, s1, 1
	v_lshlrev_b32_e32 v5, 8, v5
	v_lshlrev_b32_e32 v6, 5, v6
	v_and_b32_e32 v56, 24, v7
	v_bitop3_b32 v57, s3, -13, v3 bitop3:0xc8
	s_and_b32 s12, s8, 4
	v_or3_b32 v6, v5, v6, v56
	v_or3_b32 v3, v57, s12, v55
	v_and_or_b32 v5, s8, 2, v10
	v_lshl_or_b32 v2, v2, 8, v52
	v_lshlrev_b32_e32 v3, 8, v3
	v_lshlrev_b32_e32 v5, 5, v5
	s_lshl_b32 s11, s2, 10
	v_lshl_or_b32 v4, v4, 8, v53
	v_or3_b32 v8, v3, v5, v56
	v_ashrrev_i32_e32 v3, 31, v2
	s_add_i32 s2, s11, 0
	v_lshl_add_u64 v[40:41], v[2:3], 1, s[4:5]
	v_ashrrev_i32_e32 v5, 31, v4
	s_add_i32 s41, 0, 0x10000
	s_waitcnt vmcnt(0) lgkmcnt(0)
	s_barrier
	s_mov_b32 m0, s2
	v_lshl_add_u64 v[36:37], v[4:5], 1, s[4:5]
	v_ashrrev_i32_e32 v7, 31, v6
	s_add_i32 s3, s41, s11
	global_load_lds_dwordx4 v[40:41], off
	s_add_i32 m0, s2, 0x2000
	v_lshl_add_u64 v[38:39], v[6:7], 1, s[6:7]
	v_ashrrev_i32_e32 v9, 31, v8
	global_load_lds_dwordx4 v[36:37], off
	s_mov_b32 m0, s3
	v_lshl_add_u64 v[34:35], v[8:9], 1, s[6:7]
	global_load_lds_dwordx4 v[38:39], off
	s_add_i32 m0, s3, 0x2000
	s_mov_b64 s[16:17], 0x8000
	global_load_lds_dwordx4 v[34:35], off
	v_lshl_add_u64 v[2:3], v[40:41], 0, s[16:17]
	s_add_i32 m0, s2, 0x4000
	s_mov_b64 s[14:15], 0x10000
	global_load_lds_dwordx4 v[2:3], off
	v_lshl_add_u64 v[2:3], v[36:37], 0, s[16:17]
	s_add_i32 m0, s2, 0x6000
	v_lshlrev_b32_e32 v58, 4, v50
	global_load_lds_dwordx4 v[2:3], off
	v_lshl_add_u64 v[2:3], v[40:41], 0, s[14:15]
	s_add_i32 m0, s2, 0x8000
	v_lshlrev_b32_e32 v59, 4, v10
	global_load_lds_dwordx4 v[2:3], off
	v_lshl_add_u64 v[2:3], v[36:37], 0, s[14:15]
	s_add_i32 m0, s2, 0xa000
	v_lshlrev_b32_e32 v205, 8, v0
	global_load_lds_dwordx4 v[2:3], off
	v_add_u32_e32 v0, 0, v205
	v_and_b32_e32 v2, 0xf0, v58
	v_xor_b32_e32 v2, v59, v2
	s_waitcnt vmcnt(6) lgkmcnt(0)
	s_barrier
	v_add_u32_e32 v60, v0, v2
	ds_read_b128 v[2:5], v60
	ds_read_b128 v[18:21], v60 offset:8192
	s_waitcnt lgkmcnt(0)
	v_mfma_f32_32x32x16_bf16 v[2:17], v[2:5], v[158:161], 0
	v_and_b32_e32 v61, 0xf0, v58
	v_bitop3_b32 v42, v59, v61, 32 bitop3:0x36
	v_add_u32_e32 v62, v0, v42
	ds_read_b128 v[42:45], v62
	ds_read_b128 v[46:49], v62 offset:8192
	v_bitop3_b32 v217, v59, v61, 64 bitop3:0x36
	v_add_u32_e32 v216, v0, v217
	v_bitop3_b32 v215, v59, v61, s91 bitop3:0x36
	v_mfma_f32_32x32x16_bf16 v[18:33], v[18:21], v[158:161], 0
	v_add_u32_e32 v214, v0, v215
	s_movk_i32 s8, 0x80
	v_bitop3_b32 v213, v59, v61, s8 bitop3:0x36
	v_add_u32_e32 v212, v0, v213
	s_movk_i32 s8, 0xa0
	v_bitop3_b32 v211, v59, v61, s8 bitop3:0x36
	v_add_u32_e32 v210, v0, v211
	s_waitcnt lgkmcnt(0)
	v_mfma_f32_32x32x16_bf16 v[2:17], v[42:45], v[154:157], v[2:17]
	s_movk_i32 s8, 0xc0
	v_bitop3_b32 v209, v59, v61, s8 bitop3:0x36
	v_add_u32_e32 v208, v0, v209
	s_movk_i32 s8, 0xe0
	v_and_b32_e32 v63, 63, v50
	v_bitop3_b32 v207, v59, v61, s8 bitop3:0x36
	v_lshlrev_b32_e32 v63, 3, v63
	v_mfma_f32_32x32x16_bf16 v[18:33], v[46:49], v[154:157], v[18:33]
	ds_read_b128 v[42:45], v216
	ds_read_b128 v[46:49], v216 offset:8192
	v_add_u32_e32 v206, v0, v207
	v_lshlrev_b32_e32 v0, 1, v50
	v_and_b32_e32 v0, 32, v0
	s_mov_b64 s[38:39], 0x18000
	s_add_i32 m0, s2, 0xc000
	s_and_b32 s1, s1, 1
	s_waitcnt lgkmcnt(0)
	v_mfma_f32_32x32x16_bf16 v[2:17], v[42:45], v[150:153], v[2:17]
	s_lshl_b32 s1, s1, 6
	s_and_b32 s0, s0, 64
	v_or_b32_e32 v64, 0xe0, v59
	s_movk_i32 s14, 0x4000
	s_mov_b32 s15, 1
	s_mov_b32 s18, 0x8000
	s_mov_b32 s8, 0
	v_mfma_f32_32x32x16_bf16 v[18:33], v[46:49], v[150:153], v[18:33]
	ds_read_b128 v[42:45], v214
	ds_read_b128 v[46:49], v214 offset:8192
	v_bitop3_b32 v223, v64, v205, v61 bitop3:0xde
	v_bitop3_b32 v224, v59, v205, v61 bitop3:0xde
	s_waitcnt lgkmcnt(0)
	v_mfma_f32_32x32x16_bf16 v[2:17], v[42:45], v[146:149], v[2:17]
	v_mfma_f32_32x32x16_bf16 v[18:33], v[46:49], v[146:149], v[18:33]
	ds_read_b128 v[42:45], v212
	ds_read_b128 v[46:49], v212 offset:8192
	s_waitcnt lgkmcnt(0)
	v_mfma_f32_32x32x16_bf16 v[2:17], v[42:45], v[142:145], v[2:17]
	v_mfma_f32_32x32x16_bf16 v[18:33], v[46:49], v[142:145], v[18:33]
	ds_read_b128 v[42:45], v210
	ds_read_b128 v[46:49], v210 offset:8192
	s_waitcnt lgkmcnt(0)
	v_mfma_f32_32x32x16_bf16 v[2:17], v[42:45], v[138:141], v[2:17]
	ds_read_b128 v[42:45], v208
	v_mfma_f32_32x32x16_bf16 v[18:33], v[46:49], v[138:141], v[18:33]
	ds_read_b128 v[46:49], v208 offset:8192
	s_waitcnt lgkmcnt(0)
; #define DMA_K(T, SL) do { const long t_ = (long)(T) * (KVBLK * LDK); GLDS(ks0 + t_, (lds_uptr)((__attribute__((address_space(3))) char*)kdst + (SL))); \
;     if constexpr (DK == 128) GLDS(ks1 + t_, (lds_uptr)((__attribute__((address_space(3))) char*)kdst + (SL) + 8192)); } while (0)
; #define DMA_V(T, SL) do { const long t_ = (long)(T) * (KVBLK * LDK); GLDS(vs0 + t_, (lds_uptr)((__attribute__((address_space(3))) char*)vdst + (SL))); \
;     GLDS(vs1 + t_, (lds_uptr)((__attribute__((address_space(3))) char*)vdst + (SL) + 8192)); } while (0)
; #define WBAR(N) asm volatile("s_waitcnt vmcnt(" #N ") lgkmcnt(0)\n\ts_barrier" ::: "memory")
; #define PSM(P0, P1, T, MN, AL) do { float cb_ = 0.f; \
;     if constexpr (BIAS) { const int k0_ = (T) * KVBLK; const int rmin_ = k0_ - (qlo + 31), rmax_ = k0_ + 63 - qlo; \
;       if (rmin_ >= 91) cb_ = b_pos; else if (rmax_ <= -91) cb_ = b_neg; \
;       else add_bias(P0, P1, tb, k0_ - (qlo + r32) + 256, hi); } \
;     partialSM<DK>(P0, P1, m_reg, MN, AL, cb_); } while (0)
; template <int DK, int LDK, bool BIAS, bool NOMAX> ...
;     ...
;   if constexpr (NOMAX) { TBIAS(pA0, pA1, 0); curb = cb_; alA = 1.f;
; #pragma unroll
;     for (int r = 0; r < 16; ++r) { pA0[r] = __builtin_amdgcn_exp2f(pA0[r]); pA1[r] = __builtin_amdgcn_exp2f(pA1[r]); }
;     float ps0 = 0.f;
; #pragma unroll
;     for (int r = 0; r < 16; ++r) ps0 += pA0[r] + pA1[r];
;     { auto rr = __builtin_amdgcn_permlane32_swap(__float_as_uint(ps0), __float_as_uint(ps0), false, false);
;       ps0 = __uint_as_float(rr[0]) + __uint_as_float(rr[1]); }
;     l_reg = ps0; }
;   else PSM(pA0, pA1, 0, mnA, alA);
;   DMA_K(3, 3 * SHM_K); DMA_V(1, SHM_V);
;   if constexpr (DK == 128) WBAR(4); else WBAR(3);
;   bf16x8 kf[2][2]; s16x4 vl[3], vh[3];
; #pragma unroll
;   for (int q = 0; q < 2; ++q) { const int cbq = (q * 16 + hi * 8) * 2;
;     if constexpr (DK == 128) { kf[q][0] = *reinterpret_cast<const bf16x8*>(K_lds + SHM_K + KSWZ128(r32, cbq)); kf[q][1] = *reinterpret_cast<const bf16x8*>(K_lds + SHM_K + KSWZ128(32 + r32, cbq)); }
;     else { kf[q][0] = *reinterpret_cast<const bf16x8*>(K_lds + SHM_K + KSWZ64(r32, cbq)); kf[q][1] = *reinterpret_cast<const bf16x8*>(K_lds + SHM_K + KSWZ64(32 + r32, cbq)); } }
;   int sp = 0, sj = SHM_V, sn = 2 * SHM_V;
	v_mfma_f32_32x32x16_bf16 v[2:17], v[42:45], v[130:133], v[2:17]
	v_and_b32_e32 v42, 0xc0, v58
	v_and_or_b32 v58, v63, 24, v42
	ds_read_b128 v[42:45], v206
	v_mfma_f32_32x32x16_bf16 v[18:33], v[46:49], v[130:133], v[18:33]
	v_and_b32_e32 v46, 0x100, v63
	v_or3_b32 v202, v58, v0, v46
	ds_read_b128 v[46:49], v206 offset:8192
	v_or_b32_e32 v58, 0xa0, v59
	v_or_b32_e32 v63, 0xc0, v59
	v_add_u32_e32 v204, s41, v202
	v_bitop3_b32 v221, v58, v205, v61 bitop3:0xde
	s_waitcnt lgkmcnt(0)
	v_mfma_f32_32x32x16_bf16 v[2:17], v[42:45], v[134:137], v[2:17]
	v_or_b32_e32 v42, 32, v59
	v_or_b32_e32 v43, 64, v59
	v_or_b32_e32 v44, 0x60, v59
	v_or_b32_e32 v45, 0x80, v59
	v_bitop3_b32 v218, v43, v205, v61 bitop3:0xde
	v_bitop3_b32 v219, v44, v205, v61 bitop3:0xde
	v_bitop3_b32 v220, v45, v205, v61 bitop3:0xde
	s_nop 4
	v_exp_f32_e32 v84, v4
	v_exp_f32_e32 v108, v5
	v_lshl_add_u64 v[4:5], v[40:41], 0, s[38:39]
	global_load_lds_dwordx4 v[4:5], off
	v_lshl_add_u64 v[4:5], v[36:37], 0, s[38:39]
	s_add_i32 m0, s2, 0xe000
	v_mfma_f32_32x32x16_bf16 v[18:33], v[46:49], v[134:137], v[18:33]
	global_load_lds_dwordx4 v[4:5], off
	v_lshl_add_u64 v[4:5], v[38:39], 0, s[16:17]
	s_add_i32 m0, s3, 0x4000
	v_exp_f32_e32 v82, v2
	global_load_lds_dwordx4 v[4:5], off
	v_lshl_add_u64 v[4:5], v[34:35], 0, s[16:17]
	s_add_i32 m0, s3, 0x6000
	s_nop 4
	v_exp_f32_e32 v66, v18
	global_load_lds_dwordx4 v[4:5], off
	v_exp_f32_e32 v106, v3
	v_exp_f32_e32 v0, v19
	v_exp_f32_e32 v68, v20
	v_exp_f32_e32 v110, v21
	v_add_f32_e32 v107, v82, v66
	v_pk_add_f32 v[2:3], v[106:107], v[0:1]
	v_exp_f32_e32 v86, v6
	v_exp_f32_e32 v70, v22
	v_pk_add_f32 v[2:3], v[2:3], v[2:3] op_sel_hi:[0,1]
	v_exp_f32_e32 v112, v7
	v_exp_f32_e32 v114, v23
	v_add_f32_e32 v109, v84, v68
	v_mov_b32_e32 v111, v3
	v_pk_add_f32 v[2:3], v[108:109], v[110:111]
	v_exp_f32_e32 v88, v8
	v_exp_f32_e32 v72, v24
	v_pk_add_f32 v[2:3], v[2:3], v[2:3] op_sel_hi:[0,1]
	v_exp_f32_e32 v116, v9
	v_exp_f32_e32 v118, v25
	v_add_f32_e32 v113, v86, v70
	v_mov_b32_e32 v115, v3
	v_pk_add_f32 v[2:3], v[112:113], v[114:115]
	v_exp_f32_e32 v90, v10
	v_exp_f32_e32 v74, v26
	v_pk_add_f32 v[2:3], v[2:3], v[2:3] op_sel_hi:[0,1]
	v_exp_f32_e32 v120, v11
	v_exp_f32_e32 v122, v27
	v_add_f32_e32 v117, v88, v72
	v_mov_b32_e32 v119, v3
	v_pk_add_f32 v[2:3], v[116:117], v[118:119]
	v_exp_f32_e32 v92, v12
	v_exp_f32_e32 v76, v28
	v_pk_add_f32 v[2:3], v[2:3], v[2:3] op_sel_hi:[0,1]
	v_exp_f32_e32 v124, v13
	v_exp_f32_e32 v126, v29
	v_add_f32_e32 v121, v90, v74
	v_mov_b32_e32 v123, v3
	v_pk_add_f32 v[2:3], v[120:121], v[122:123]
	v_exp_f32_e32 v94, v14
	v_exp_f32_e32 v78, v30
	v_pk_add_f32 v[2:3], v[2:3], v[2:3] op_sel_hi:[0,1]
	v_exp_f32_e32 v128, v15
	v_exp_f32_e32 v184, v31
	v_add_f32_e32 v125, v92, v76
	v_mov_b32_e32 v127, v3
	v_pk_add_f32 v[2:3], v[124:125], v[126:127]
	v_exp_f32_e32 v96, v16
	v_exp_f32_e32 v80, v32
	v_pk_add_f32 v[2:3], v[2:3], v[2:3] op_sel_hi:[0,1]
	v_exp_f32_e32 v186, v17
	v_exp_f32_e32 v188, v33
	v_add_f32_e32 v129, v94, v78
	v_mov_b32_e32 v185, v3
	v_pk_add_f32 v[2:3], v[128:129], v[184:185]
	v_add_f32_e32 v187, v96, v80
	v_pk_add_f32 v[2:3], v[2:3], v[2:3] op_sel_hi:[0,1]
	v_mov_b32_e32 v189, v3
	v_pk_add_f32 v[2:3], v[186:187], v[188:189]
	v_and_b32_e32 v4, 32, v50
	v_pk_add_f32 v[2:3], v[2:3], v[2:3] op_sel:[0,1] op_sel_hi:[1,0]
	s_waitcnt vmcnt(4) lgkmcnt(0)
	s_barrier
	ds_read_b128 v[162:165], v62 offset:24576
	ds_read_b128 v[166:169], v62 offset:16384
	ds_read_b128 v[98:101], v60 offset:24576
	ds_read_b128 v[102:105], v60 offset:16384
	v_mov_b32_e32 v3, v2
	s_nop 1
	v_permlane32_swap_b32_e32 v2, v3
	v_add_f32_e32 v203, v2, v3
	v_or3_b32 v2, v57, v55, s12
	v_lshl_or_b32 v2, v2, 8, s1
	v_or3_b32 v2, v2, v4, v56
	v_ashrrev_i32_e32 v3, 31, v2
	v_lshlrev_b64 v[170:171], 1, v[2:3]
	v_or_b32_e32 v2, s9, v55
	v_or3_b32 v2, v2, s10, v54
	v_lshl_or_b32 v2, v2, 8, s0
	v_or3_b32 v2, v2, v4, v56
	v_ashrrev_i32_e32 v3, 31, v2
	s_add_i32 s0, s11, 0x2000
	v_lshlrev_b32_e32 v4, 8, v51
	v_lshlrev_b64 v[172:173], 1, v[2:3]
	v_or3_b32 v2, s0, v4, v53
	v_ashrrev_i32_e32 v3, 31, v2
	v_lshlrev_b64 v[180:181], 1, v[2:3]
	v_or3_b32 v2, s11, v4, v52
	v_ashrrev_i32_e32 v3, 31, v2
	v_lshlrev_b64 v[182:183], 1, v[2:3]
	v_mov_b32_e32 v2, 0
	v_bitop3_b32 v222, v63, v205, v61 bitop3:0xde
	v_bitop3_b32 v225, v42, v205, v61 bitop3:0xde
	s_mov_b64 s[0:1], s[42:43]
	s_mov_b32 s16, 0x8000
	v_mov_b32_e32 v3, v2
	v_mov_b32_e32 v4, v2
	v_mov_b32_e32 v5, v2
	v_mov_b32_e32 v6, v2
	v_mov_b32_e32 v7, v2
	v_mov_b32_e32 v8, v2
	v_mov_b32_e32 v9, v2
	v_mov_b32_e32 v10, v2
	v_mov_b32_e32 v11, v2
	v_mov_b32_e32 v12, v2
	v_mov_b32_e32 v13, v2
	v_mov_b32_e32 v14, v2
	v_mov_b32_e32 v15, v2
	v_mov_b32_e32 v16, v2
	v_mov_b32_e32 v17, v2
	v_mov_b32_e32 v18, v2
	v_mov_b32_e32 v19, v2
	v_mov_b32_e32 v20, v2
	v_mov_b32_e32 v21, v2
	v_mov_b32_e32 v22, v2
	v_mov_b32_e32 v23, v2
	v_mov_b32_e32 v24, v2
	v_mov_b32_e32 v25, v2
	v_mov_b32_e32 v26, v2
	v_mov_b32_e32 v27, v2
	v_mov_b32_e32 v28, v2
	v_mov_b32_e32 v29, v2
	v_mov_b32_e32 v30, v2
	v_mov_b32_e32 v31, v2
	v_mov_b32_e32 v32, v2
	v_mov_b32_e32 v33, v2
	v_mov_b32_e32 v34, v2
	v_mov_b32_e32 v35, v2
	v_mov_b32_e32 v36, v2
	v_mov_b32_e32 v37, v2
	v_mov_b32_e32 v38, v2
	v_mov_b32_e32 v39, v2
	v_mov_b32_e32 v40, v2
	v_mov_b32_e32 v41, v2
	v_mov_b32_e32 v42, v2
	v_mov_b32_e32 v43, v2
	v_mov_b32_e32 v44, v2
	v_mov_b32_e32 v45, v2
	v_mov_b32_e32 v46, v2
	v_mov_b32_e32 v47, v2
	v_mov_b32_e32 v48, v2
	v_mov_b32_e32 v49, v2
	v_mov_b32_e32 v50, v2
	v_mov_b32_e32 v51, v2
	v_mov_b32_e32 v52, v2
	v_mov_b32_e32 v53, v2
	v_mov_b32_e32 v54, v2
	v_mov_b32_e32 v55, v2
	v_mov_b32_e32 v56, v2
	v_mov_b32_e32 v57, v2
	v_mov_b32_e32 v58, v2
	v_mov_b32_e32 v59, v2
	v_mov_b32_e32 v60, v2
	v_mov_b32_e32 v61, v2
	v_mov_b32_e32 v62, v2
	v_mov_b32_e32 v63, v2
	v_mov_b32_e32 v64, v2
	v_mov_b32_e32 v65, v2
	v_mov_b32_e32 v67, v0
	v_mov_b32_e32 v69, v110
	v_mov_b32_e32 v71, v114
	v_mov_b32_e32 v73, v118
	v_mov_b32_e32 v75, v122
	v_mov_b32_e32 v77, v126
	v_mov_b32_e32 v79, v184
	v_mov_b32_e32 v81, v188
	v_mov_b32_e32 v83, v106
	v_mov_b32_e32 v85, v108
	v_mov_b32_e32 v87, v112
	v_mov_b32_e32 v89, v116
	v_mov_b32_e32 v91, v120
	v_mov_b32_e32 v93, v124
	v_mov_b32_e32 v95, v128
	v_mov_b32_e32 v97, v186

; __device__ __forceinline__ int v_rd_base(int lane) { return ((lane & 3) << 3) | (((lane >> 2) & 3) << 6) | (((lane >> 4) & 1) << 5) | (((lane >> 5) & 1) << 8); }
; template <int DK>
; __device__ __forceinline__ void qkt(f32x16& p0, f32x16& p1, const char* Ks, const bf16x8* qr, int r32, int hi) {
;   p0 = f32x16{}; p1 = f32x16{};
; #pragma unroll
;   for (int d0 = 0; d0 < DK / 16; ++d0) { const int cb = (d0 * 16 + hi * 8) * 2;
;     bf16x8 b0, b1;
;     if constexpr (DK == 128) { b0 = *reinterpret_cast<const bf16x8*>(Ks + KSWZ128(r32, cb)); b1 = *reinterpret_cast<const bf16x8*>(Ks + KSWZ128(32 + r32, cb)); }
;     else { b0 = *reinterpret_cast<const bf16x8*>(Ks + KSWZ64(r32, cb)); b1 = *reinterpret_cast<const bf16x8*>(Ks + KSWZ64(32 + r32, cb)); }
;     p0 = __builtin_amdgcn_mfma_f32_32x32x16_bf16(b0, qr[d0], p0, 0, 0, 0);
;     p1 = __builtin_amdgcn_mfma_f32_32x32x16_bf16(b1, qr[d0], p1, 0, 0, 0); }
; template <int DK, int LDK, bool BIAS, bool NOMAX> ...
;     ...
;   if constexpr (DK == 128) { { const int r = 4 * wid + (lane >> 4), c = (lane & 15) ^ (r & 7); koff0 = r * LDK + c * 8; }
;                              { const int r = 4 * (wid + 8) + (lane >> 4), c = (lane & 15) ^ (r & 7); koff1 = r * LDK + c * 8; } }
;   else { const int r = 8 * wid + (lane >> 3), c = (lane & 7) ^ ((r >> 1) & 7); koff0 = r * LDK + c * 8; }
;   { const int st = 2 * wid + (lane >> 5), kk = (st >> 2) * 8 + ((lane & 31) >> 2), k = (kk & ~0xC) | ((kk & 4) << 1) | ((kk & 8) >> 1); voff0 = k * LDK + (st & 3) * 32 + (lane & 3) * 8; }
;   { const int st = 2 * (wid + 8) + (lane >> 5), kk = (st >> 2) * 8 + ((lane & 31) >> 2), k = (kk & ~0xC) | ((kk & 4) << 1) | ((kk & 8) >> 1); voff1 = k * LDK + (st & 3) * 32 + (lane & 3) * 8; }
;   const bf16_t* ks0 = Kh + koff0; const bf16_t* ks1 = Kh + koff1; const bf16_t* vs0 = Vh + voff0; const bf16_t* vs1 = Vh + voff1;
;   const lds_uptr kdst = (lds_uptr)(K_lds + wid * 1024), vdst = (lds_uptr)(V_lds + wid * 1024);
;     ...
;   float curb = 0.f;
;   f32x16 pA0, pA1, pB0, pB1; float mnA, alA, alB; bf16x8 pa[4]; const int NT = seq / KVBLK;
;   const lds_cptr vp0 = (lds_cptr)V_lds + v_rd_base(lane);
;   const int vb0 = (int)(uintptr_t)V_lds + v_rd_base(lane);
;   WBAR(0);
;   DMA_K(0, 0); DMA_V(0, 0); DMA_K(1, SHM_K); DMA_K(2, 2 * SHM_K);
;   if constexpr (DK == 128) WBAR(6); else WBAR(4);
.LBB0_461:
	s_or_b64 exec, exec, s[0:1]
	s_lshr_b32 s3, s21, 4
	s_and_b32 s0, s20, 0xfffff000
	s_ashr_i32 s1, s0, 31
	s_and_b32 s3, s3, 4
	s_lshl_b64 s[0:1], s[0:1], 9
	s_lshl_b32 s3, s3, 6
	s_or_b32 s0, s0, s3
	s_add_u32 s42, s86, s0
	s_addc_u32 s43, s87, s1
	s_ashr_i32 s41, s40, 31
	s_lshl_b64 s[0:1], s[40:41], 9
	v_readlane_b32 s4, v249, 44
	v_readlane_b32 s5, v249, 45
	s_add_u32 s3, s4, s0
	s_addc_u32 s7, s5, s1
	v_readlane_b32 s4, v249, 42
	v_readlane_b32 s5, v249, 43
	s_add_u32 s0, s4, s0
	s_addc_u32 s1, s5, s1
	s_lshl_b32 s2, s2, 6
	s_and_b32 s2, s2, 0x100
	s_add_u32 s4, s0, s2
	s_addc_u32 s5, s1, 0
	v_mov_b32_e32 v50, v176
	s_add_u32 s6, s3, s2
	s_addc_u32 s7, s7, 0
	v_readfirstlane_b32 s0, v50
	s_ashr_i32 s2, s0, 6
	v_bfe_u32 v51, v50, 4, 2
	v_lshl_or_b32 v2, s2, 2, v51
	v_and_b32_e32 v3, 15, v50
	s_add_i32 s1, s2, 8
	v_and_b32_e32 v0, 31, v50
	v_bitop3_b32 v4, v2, v3, 15 bitop3:0x6c
	s_lshl_b32 s3, s1, 2
	s_ashr_i32 s10, s0, 4
	v_lshlrev_b32_e32 v52, 3, v4
	v_or_b32_e32 v4, s3, v51
	s_and_b32 s9, s10, -16
	v_bfe_u32 v54, v0, 2, 2
	v_lshrrev_b32_e32 v6, 1, v50
	s_lshr_b32 s10, s10, 1
	v_bfe_u32 v10, v50, 5, 1
	v_bitop3_b32 v3, v4, v3, 15 bitop3:0x6c
	s_lshl_b32 s8, s2, 1
	v_or_b32_e32 v5, s9, v54
	v_and_b32_e32 v55, 8, v6
	s_and_b32 s10, s10, 4
	v_lshlrev_b32_e32 v53, 3, v3
	v_bfe_u32 v3, v50, 2, 3
	v_or3_b32 v5, v5, s10, v55
	v_and_or_b32 v6, s8, 2, v10
	v_lshlrev_b32_e32 v7, 3, v50
	s_lshl_b32 s8, s1, 1
	v_lshlrev_b32_e32 v5, 8, v5
	v_lshlrev_b32_e32 v6, 5, v6
	v_and_b32_e32 v56, 24, v7
	v_bitop3_b32 v57, s3, -13, v3 bitop3:0xc8
	s_and_b32 s12, s8, 4
	v_or3_b32 v6, v5, v6, v56
	v_or3_b32 v3, v57, s12, v55
	v_and_or_b32 v5, s8, 2, v10
	v_lshl_or_b32 v2, v2, 8, v52
	v_lshlrev_b32_e32 v3, 8, v3
	v_lshlrev_b32_e32 v5, 5, v5
	s_lshl_b32 s11, s2, 10
	v_lshl_or_b32 v4, v4, 8, v53
	v_or3_b32 v8, v3, v5, v56
	v_ashrrev_i32_e32 v3, 31, v2
	s_add_i32 s2, s11, 0
	v_lshl_add_u64 v[40:41], v[2:3], 1, s[4:5]
	v_ashrrev_i32_e32 v5, 31, v4
	s_add_i32 s41, 0, 0x10000
	s_waitcnt vmcnt(0) lgkmcnt(0)
	s_barrier
	s_mov_b32 m0, s2
	v_lshl_add_u64 v[36:37], v[4:5], 1, s[4:5]
	v_ashrrev_i32_e32 v7, 31, v6
	s_add_i32 s3, s41, s11
	global_load_lds_dwordx4 v[40:41], off
	s_add_i32 m0, s2, 0x2000
	v_lshl_add_u64 v[38:39], v[6:7], 1, s[6:7]
	v_ashrrev_i32_e32 v9, 31, v8
	global_load_lds_dwordx4 v[36:37], off
	s_mov_b32 m0, s3
	v_lshl_add_u64 v[34:35], v[8:9], 1, s[6:7]
	global_load_lds_dwordx4 v[38:39], off
	s_add_i32 m0, s3, 0x2000
	s_mov_b64 s[16:17], 0x8000
	global_load_lds_dwordx4 v[34:35], off
	v_lshl_add_u64 v[2:3], v[40:41], 0, s[16:17]
	s_add_i32 m0, s2, 0x4000
	s_mov_b64 s[14:15], 0x10000
	global_load_lds_dwordx4 v[2:3], off
	v_lshl_add_u64 v[2:3], v[36:37], 0, s[16:17]
	s_add_i32 m0, s2, 0x6000
	v_lshlrev_b32_e32 v58, 4, v50
	global_load_lds_dwordx4 v[2:3], off
	v_lshl_add_u64 v[2:3], v[40:41], 0, s[14:15]
	s_add_i32 m0, s2, 0x8000
	v_lshlrev_b32_e32 v59, 4, v10
	global_load_lds_dwordx4 v[2:3], off
	v_lshl_add_u64 v[2:3], v[36:37], 0, s[14:15]
	s_add_i32 m0, s2, 0xa000
	v_lshlrev_b32_e32 v205, 8, v0
	global_load_lds_dwordx4 v[2:3], off
	v_add_u32_e32 v0, 0, v205
	v_and_b32_e32 v2, 0xf0, v58
	v_xor_b32_e32 v2, v59, v2
	s_waitcnt vmcnt(6) lgkmcnt(0)
	s_barrier
	v_add_u32_e32 v60, v0, v2
	ds_read_b128 v[2:5], v60
	ds_read_b128 v[18:21], v60 offset:8192
	s_waitcnt lgkmcnt(0)
	v_mfma_f32_32x32x16_bf16 v[2:17], v[2:5], v[158:161], 0
	v_and_b32_e32 v61, 0xf0, v58
	v_bitop3_b32 v42, v59, v61, 32 bitop3:0x36
	v_add_u32_e32 v62, v0, v42
	ds_read_b128 v[42:45], v62
	ds_read_b128 v[46:49], v62 offset:8192
	v_bitop3_b32 v217, v59, v61, 64 bitop3:0x36
	v_add_u32_e32 v216, v0, v217
	v_bitop3_b32 v215, v59, v61, s91 bitop3:0x36
	v_mfma_f32_32x32x16_bf16 v[18:33], v[18:21], v[158:161], 0
	v_add_u32_e32 v214, v0, v215
	s_movk_i32 s8, 0x80
	v_bitop3_b32 v213, v59, v61, s8 bitop3:0x36
	v_add_u32_e32 v212, v0, v213
	s_movk_i32 s8, 0xa0
	v_bitop3_b32 v211, v59, v61, s8 bitop3:0x36
	v_add_u32_e32 v210, v0, v211
	s_waitcnt lgkmcnt(0)
	v_mfma_f32_32x32x16_bf16 v[2:17], v[42:45], v[154:157], v[2:17]
	s_movk_i32 s8, 0xc0
	v_bitop3_b32 v209, v59, v61, s8 bitop3:0x36
	v_add_u32_e32 v208, v0, v209
	s_movk_i32 s8, 0xe0
	v_and_b32_e32 v63, 63, v50
	v_bitop3_b32 v207, v59, v61, s8 bitop3:0x36
	v_lshlrev_b32_e32 v63, 3, v63
	v_mfma_f32_32x32x16_bf16 v[18:33], v[46:49], v[154:157], v[18:33]
	ds_read_b128 v[42:45], v216
	ds_read_b128 v[46:49], v216 offset:8192
	v_add_u32_e32 v206, v0, v207
	v_lshlrev_b32_e32 v64, 1, v50
	v_and_b32_e32 v0, 32, v64
	s_mov_b64 s[38:39], 0x18000
	s_add_i32 m0, s2, 0xc000
	s_and_b32 s1, s1, 1
	s_waitcnt lgkmcnt(0)
	v_mfma_f32_32x32x16_bf16 v[2:17], v[42:45], v[150:153], v[2:17]
	s_lshl_b32 s1, s1, 6
	s_and_b32 s0, s0, 64
	v_or_b32_e32 v64, 0xe0, v59
	s_mov_b32 s14, 1
	s_movk_i32 s15, 0x4000
	s_mov_b32 s18, 0x8000
	s_mov_b32 s8, 0
	v_mfma_f32_32x32x16_bf16 v[18:33], v[46:49], v[150:153], v[18:33]
	ds_read_b128 v[42:45], v214
	ds_read_b128 v[46:49], v214 offset:8192
	v_bitop3_b32 v223, v64, v205, v61 bitop3:0xde
	v_bitop3_b32 v224, v59, v205, v61 bitop3:0xde
	s_waitcnt lgkmcnt(0)
	v_mfma_f32_32x32x16_bf16 v[2:17], v[42:45], v[146:149], v[2:17]
	v_mfma_f32_32x32x16_bf16 v[18:33], v[46:49], v[146:149], v[18:33]
	ds_read_b128 v[42:45], v212
	ds_read_b128 v[46:49], v212 offset:8192
	s_waitcnt lgkmcnt(0)
	v_mfma_f32_32x32x16_bf16 v[2:17], v[42:45], v[142:145], v[2:17]
	v_mfma_f32_32x32x16_bf16 v[18:33], v[46:49], v[142:145], v[18:33]
	ds_read_b128 v[42:45], v210
	ds_read_b128 v[46:49], v210 offset:8192
	s_waitcnt lgkmcnt(0)
	v_mfma_f32_32x32x16_bf16 v[2:17], v[42:45], v[138:141], v[2:17]
	ds_read_b128 v[42:45], v208
	v_mfma_f32_32x32x16_bf16 v[18:33], v[46:49], v[138:141], v[18:33]
	ds_read_b128 v[46:49], v208 offset:8192
	s_waitcnt lgkmcnt(0)
; #define DMA_K(T, SL) do { const long t_ = (long)(T) * (KVBLK * LDK); GLDS(ks0 + t_, (lds_uptr)((__attribute__((address_space(3))) char*)kdst + (SL))); \
;     if constexpr (DK == 128) GLDS(ks1 + t_, (lds_uptr)((__attribute__((address_space(3))) char*)kdst + (SL) + 8192)); } while (0)
; #define DMA_V(T, SL) do { const long t_ = (long)(T) * (KVBLK * LDK); GLDS(vs0 + t_, (lds_uptr)((__attribute__((address_space(3))) char*)vdst + (SL))); \
;     GLDS(vs1 + t_, (lds_uptr)((__attribute__((address_space(3))) char*)vdst + (SL) + 8192)); } while (0)
; #define WBAR(N) asm volatile("s_waitcnt vmcnt(" #N ") lgkmcnt(0)\n\ts_barrier" ::: "memory")
; #define PSM(P0, P1, T, MN, AL) do { float cb_ = 0.f; \
;     if constexpr (BIAS) { const int k0_ = (T) * KVBLK; const int rmin_ = k0_ - (qlo + 31), rmax_ = k0_ + 63 - qlo; \
;       if (rmin_ >= 91) cb_ = b_pos; else if (rmax_ <= -91) cb_ = b_neg; \
;       else add_bias(P0, P1, tb, k0_ - (qlo + r32) + 256, hi); } \
;     partialSM<DK>(P0, P1, m_reg, MN, AL, cb_); } while (0)
; template <int DK, int LDK, bool BIAS, bool NOMAX> ...
;     ...
;   if constexpr (NOMAX) { TBIAS(pA0, pA1, 0); curb = cb_; alA = 1.f;
; #pragma unroll
;     for (int r = 0; r < 16; ++r) { pA0[r] = __builtin_amdgcn_exp2f(pA0[r]); pA1[r] = __builtin_amdgcn_exp2f(pA1[r]); }
;     float ps0 = 0.f;
; #pragma unroll
;     for (int r = 0; r < 16; ++r) ps0 += pA0[r] + pA1[r];
;     { auto rr = __builtin_amdgcn_permlane32_swap(__float_as_uint(ps0), __float_as_uint(ps0), false, false);
;       ps0 = __uint_as_float(rr[0]) + __uint_as_float(rr[1]); }
;     l_reg = ps0; }
;   else PSM(pA0, pA1, 0, mnA, alA);
;   DMA_K(3, 3 * SHM_K); DMA_V(1, SHM_V);
;   if constexpr (DK == 128) WBAR(4); else WBAR(3);
;   bf16x8 kf[2][2]; s16x4 vl[3], vh[3];
; #pragma unroll
;   for (int q = 0; q < 2; ++q) { const int cbq = (q * 16 + hi * 8) * 2;
;     if constexpr (DK == 128) { kf[q][0] = *reinterpret_cast<const bf16x8*>(K_lds + SHM_K + KSWZ128(r32, cbq)); kf[q][1] = *reinterpret_cast<const bf16x8*>(K_lds + SHM_K + KSWZ128(32 + r32, cbq)); }
;     else { kf[q][0] = *reinterpret_cast<const bf16x8*>(K_lds + SHM_K + KSWZ64(r32, cbq)); kf[q][1] = *reinterpret_cast<const bf16x8*>(K_lds + SHM_K + KSWZ64(32 + r32, cbq)); } }
;   int sp = 0, sj = SHM_V, sn = 2 * SHM_V;
	v_mfma_f32_32x32x16_bf16 v[2:17], v[42:45], v[130:133], v[2:17]
	v_and_b32_e32 v42, 0xc0, v58
	v_and_or_b32 v58, v63, 24, v42
	ds_read_b128 v[42:45], v206
	v_mfma_f32_32x32x16_bf16 v[18:33], v[46:49], v[130:133], v[18:33]
	v_and_b32_e32 v46, 0x100, v63
	v_or3_b32 v202, v58, v0, v46
	ds_read_b128 v[46:49], v206 offset:8192
	v_or_b32_e32 v58, 0xa0, v59
	v_or_b32_e32 v63, 0xc0, v59
	v_add_u32_e32 v204, s41, v202
	v_bitop3_b32 v221, v58, v205, v61 bitop3:0xde
	s_waitcnt lgkmcnt(0)
	v_mfma_f32_32x32x16_bf16 v[2:17], v[42:45], v[134:137], v[2:17]
	v_or_b32_e32 v42, 32, v59
	v_or_b32_e32 v43, 64, v59
	v_or_b32_e32 v44, 0x60, v59
	v_or_b32_e32 v45, 0x80, v59
	v_bitop3_b32 v218, v43, v205, v61 bitop3:0xde
	v_bitop3_b32 v219, v44, v205, v61 bitop3:0xde
	v_bitop3_b32 v220, v45, v205, v61 bitop3:0xde
	s_nop 4
	v_exp_f32_e32 v84, v4
	v_exp_f32_e32 v108, v5
	v_lshl_add_u64 v[4:5], v[40:41], 0, s[38:39]
	global_load_lds_dwordx4 v[4:5], off
	v_lshl_add_u64 v[4:5], v[36:37], 0, s[38:39]
	s_add_i32 m0, s2, 0xe000
	v_mfma_f32_32x32x16_bf16 v[18:33], v[46:49], v[134:137], v[18:33]
	global_load_lds_dwordx4 v[4:5], off
	v_lshl_add_u64 v[4:5], v[38:39], 0, s[16:17]
	s_add_i32 m0, s3, 0x4000
	v_exp_f32_e32 v82, v2
	global_load_lds_dwordx4 v[4:5], off
	v_lshl_add_u64 v[4:5], v[34:35], 0, s[16:17]
	s_add_i32 m0, s3, 0x6000
	s_nop 4
	v_exp_f32_e32 v66, v18
	global_load_lds_dwordx4 v[4:5], off
	v_exp_f32_e32 v106, v3
	v_exp_f32_e32 v0, v19
	v_exp_f32_e32 v68, v20
	v_exp_f32_e32 v110, v21
	v_add_f32_e32 v107, v82, v66
	v_pk_add_f32 v[2:3], v[106:107], v[0:1]
	v_exp_f32_e32 v86, v6
	v_exp_f32_e32 v70, v22
	v_pk_add_f32 v[2:3], v[2:3], v[2:3] op_sel_hi:[0,1]
	v_exp_f32_e32 v112, v7
	v_exp_f32_e32 v114, v23
	v_add_f32_e32 v109, v84, v68
	v_mov_b32_e32 v111, v3
	v_pk_add_f32 v[2:3], v[108:109], v[110:111]
	v_exp_f32_e32 v88, v8
	v_exp_f32_e32 v72, v24
	v_pk_add_f32 v[2:3], v[2:3], v[2:3] op_sel_hi:[0,1]
	v_exp_f32_e32 v116, v9
	v_exp_f32_e32 v118, v25
	v_add_f32_e32 v113, v86, v70
	v_mov_b32_e32 v115, v3
	v_pk_add_f32 v[2:3], v[112:113], v[114:115]
	v_exp_f32_e32 v90, v10
	v_exp_f32_e32 v74, v26
	v_pk_add_f32 v[2:3], v[2:3], v[2:3] op_sel_hi:[0,1]
	v_exp_f32_e32 v120, v11
	v_exp_f32_e32 v122, v27
	v_add_f32_e32 v117, v88, v72
	v_mov_b32_e32 v119, v3
	v_pk_add_f32 v[2:3], v[116:117], v[118:119]
	v_exp_f32_e32 v92, v12
	v_exp_f32_e32 v76, v28
	v_pk_add_f32 v[2:3], v[2:3], v[2:3] op_sel_hi:[0,1]
	v_exp_f32_e32 v124, v13
	v_exp_f32_e32 v126, v29
	v_add_f32_e32 v121, v90, v74
	v_mov_b32_e32 v123, v3
	v_pk_add_f32 v[2:3], v[120:121], v[122:123]
	v_exp_f32_e32 v94, v14
	v_exp_f32_e32 v78, v30
	v_pk_add_f32 v[2:3], v[2:3], v[2:3] op_sel_hi:[0,1]
	v_exp_f32_e32 v128, v15
	v_exp_f32_e32 v184, v31
	v_add_f32_e32 v125, v92, v76
	v_mov_b32_e32 v127, v3
	v_pk_add_f32 v[2:3], v[124:125], v[126:127]
	v_exp_f32_e32 v96, v16
	v_exp_f32_e32 v80, v32
	v_pk_add_f32 v[2:3], v[2:3], v[2:3] op_sel_hi:[0,1]
	v_exp_f32_e32 v186, v17
	v_exp_f32_e32 v188, v33
	v_add_f32_e32 v129, v94, v78
	v_mov_b32_e32 v185, v3
	v_pk_add_f32 v[2:3], v[128:129], v[184:185]
	v_add_f32_e32 v187, v96, v80
	v_pk_add_f32 v[2:3], v[2:3], v[2:3] op_sel_hi:[0,1]
	v_mov_b32_e32 v189, v3
	v_pk_add_f32 v[2:3], v[186:187], v[188:189]
	v_and_b32_e32 v4, 32, v50
	v_pk_add_f32 v[2:3], v[2:3], v[2:3] op_sel:[0,1] op_sel_hi:[1,0]
	s_waitcnt vmcnt(4) lgkmcnt(0)
	s_barrier
	ds_read_b128 v[162:165], v62 offset:24576
	ds_read_b128 v[166:169], v62 offset:16384
	ds_read_b128 v[98:101], v60 offset:24576
	ds_read_b128 v[102:105], v60 offset:16384
	v_mov_b32_e32 v3, v2
	s_nop 1
	v_permlane32_swap_b32_e32 v2, v3
	v_add_f32_e32 v203, v2, v3
	v_or3_b32 v2, v57, v55, s12
	v_lshl_or_b32 v2, v2, 8, s1
	v_or3_b32 v2, v2, v4, v56
	v_ashrrev_i32_e32 v3, 31, v2
	v_lshlrev_b64 v[170:171], 1, v[2:3]
	v_or_b32_e32 v2, s9, v55
	v_or3_b32 v2, v2, s10, v54
	v_lshl_or_b32 v2, v2, 8, s0
	v_or3_b32 v2, v2, v4, v56
	v_ashrrev_i32_e32 v3, 31, v2
	s_add_i32 s0, s11, 0x2000
	v_lshlrev_b32_e32 v4, 8, v51
	v_lshlrev_b64 v[172:173], 1, v[2:3]
	v_or3_b32 v2, s0, v4, v53
	v_ashrrev_i32_e32 v3, 31, v2
	v_lshlrev_b64 v[180:181], 1, v[2:3]
	v_or3_b32 v2, s11, v4, v52
	v_ashrrev_i32_e32 v3, 31, v2
	v_lshlrev_b64 v[182:183], 1, v[2:3]
	v_mov_b32_e32 v2, 0
	v_bitop3_b32 v222, v63, v205, v61 bitop3:0xde
	v_bitop3_b32 v225, v42, v205, v61 bitop3:0xde
	s_mov_b64 s[0:1], s[42:43]
	s_mov_b32 s16, 0x8000
	v_mov_b32_e32 v3, v2
	v_mov_b32_e32 v4, v2
	v_mov_b32_e32 v5, v2
	v_mov_b32_e32 v6, v2
	v_mov_b32_e32 v7, v2
	v_mov_b32_e32 v8, v2
	v_mov_b32_e32 v9, v2
	v_mov_b32_e32 v10, v2
	v_mov_b32_e32 v11, v2
	v_mov_b32_e32 v12, v2
	v_mov_b32_e32 v13, v2
	v_mov_b32_e32 v14, v2
	v_mov_b32_e32 v15, v2
	v_mov_b32_e32 v16, v2
	v_mov_b32_e32 v17, v2
	v_mov_b32_e32 v18, v2
	v_mov_b32_e32 v19, v2
	v_mov_b32_e32 v20, v2
	v_mov_b32_e32 v21, v2
	v_mov_b32_e32 v22, v2
	v_mov_b32_e32 v23, v2
	v_mov_b32_e32 v24, v2
	v_mov_b32_e32 v25, v2
	v_mov_b32_e32 v26, v2
	v_mov_b32_e32 v27, v2
	v_mov_b32_e32 v28, v2
	v_mov_b32_e32 v29, v2
	v_mov_b32_e32 v30, v2
	v_mov_b32_e32 v31, v2
	v_mov_b32_e32 v32, v2
	v_mov_b32_e32 v33, v2
	v_mov_b32_e32 v34, v2
	v_mov_b32_e32 v35, v2
	v_mov_b32_e32 v36, v2
	v_mov_b32_e32 v37, v2
	v_mov_b32_e32 v38, v2
	v_mov_b32_e32 v39, v2
	v_mov_b32_e32 v40, v2
	v_mov_b32_e32 v41, v2
	v_mov_b32_e32 v42, v2
	v_mov_b32_e32 v43, v2
	v_mov_b32_e32 v44, v2
	v_mov_b32_e32 v45, v2
	v_mov_b32_e32 v46, v2
	v_mov_b32_e32 v47, v2
	v_mov_b32_e32 v48, v2
	v_mov_b32_e32 v49, v2
	v_mov_b32_e32 v50, v2
	v_mov_b32_e32 v51, v2
	v_mov_b32_e32 v52, v2
	v_mov_b32_e32 v53, v2
	v_mov_b32_e32 v54, v2
	v_mov_b32_e32 v55, v2
	v_mov_b32_e32 v56, v2
	v_mov_b32_e32 v57, v2
	v_mov_b32_e32 v58, v2
	v_mov_b32_e32 v59, v2
	v_mov_b32_e32 v60, v2
	v_mov_b32_e32 v61, v2
	v_mov_b32_e32 v62, v2
	v_mov_b32_e32 v63, v2
	v_mov_b32_e32 v64, v2
	v_mov_b32_e32 v65, v2
	v_mov_b32_e32 v67, v0
	v_mov_b32_e32 v69, v110
	v_mov_b32_e32 v71, v114
	v_mov_b32_e32 v73, v118
	v_mov_b32_e32 v75, v122
	v_mov_b32_e32 v77, v126
	v_mov_b32_e32 v79, v184
	v_mov_b32_e32 v81, v188
	v_mov_b32_e32 v83, v106
	v_mov_b32_e32 v85, v108
	v_mov_b32_e32 v87, v112
	v_mov_b32_e32 v89, v116
	v_mov_b32_e32 v91, v120
	v_mov_b32_e32 v93, v124
	v_mov_b32_e32 v95, v128
	v_mov_b32_e32 v97, v186
